# before-barrier conversion slices as v51, padded (11 s_nop after the drain) so that the code after the scan phase sits at the same addresses mod 128 as in v46
# baseline (speedup 1.0000x reference)
; __device__ __forceinline__ void rwkv_scan_phase(Frame& F, const bf16* RKV, const float* WAG, const bf16* AGB, const float* k_k, const float* k_a, const float* r_k, bf16* Y, float* BS, float* ST2) {
;     ...
;             ST_FLUSH(NCH - 1);
.Lcsd_dskip:
	s_nop 0
	s_nop 0
	s_nop 0
	s_nop 0
	s_nop 0
	s_nop 0
	s_nop 0
	s_nop 0
	s_nop 0
	s_nop 0
	s_nop 0
	ds_read_b128 v[0:3], v169
	v_lshl_add_u64 v[4:5], s[44:45], 1, v[106:107]
	s_lshl_b32 s0, s0, 1
	v_lshl_add_u64 v[4:5], v[4:5], 0, s[0:1]
	s_waitcnt lgkmcnt(0)
	v_cvt_pk_bf16_f32 v6, v0, v1
	v_cvt_pk_bf16_f32 v7, v2, v3
	v_lshl_add_u64 v[4:5], v[4:5], 0, v[92:93]
	global_store_dwordx2 v[4:5], v[6:7], off
	v_mul_f32_e32 v5, v0, v0
	v_mul_f32_e32 v7, v1, v1
	v_mul_f32_e32 v9, v2, v2
	v_mul_f32_e32 v11, v3, v3
	v_mov_b32_e32 v4, v0
	v_mov_b32_e32 v6, v1
	v_mov_b32_e32 v8, v2
	v_mov_b32_e32 v10, v3
	v_pk_add_f32 v[0:1], v[4:5], v[6:7]
	v_pk_add_f32 v[2:3], v[8:9], v[10:11]
	s_nop 0
	v_pk_add_f32 v[0:1], v[0:1], v[2:3]
	s_nop 1
	v_mov_b32_dpp v2, v0 quad_perm:[1,0,3,2] row_mask:0xf bank_mask:0xf bound_ctrl:1
	v_mov_b32_dpp v3, v1 quad_perm:[1,0,3,2] row_mask:0xf bank_mask:0xf bound_ctrl:1
	v_pk_add_f32 v[0:1], v[0:1], v[2:3]
	s_nop 1
	v_mov_b32_dpp v2, v0 quad_perm:[2,3,0,1] row_mask:0xf bank_mask:0xf bound_ctrl:1
	v_mov_b32_dpp v3, v1 quad_perm:[2,3,0,1] row_mask:0xf bank_mask:0xf bound_ctrl:1
	v_pk_add_f32 v[0:1], v[0:1], v[2:3]
	s_nop 1
	v_mov_b32_dpp v2, v0 row_half_mirror row_mask:0xf bank_mask:0xf bound_ctrl:1
	v_mov_b32_dpp v3, v1 row_half_mirror row_mask:0xf bank_mask:0xf bound_ctrl:1
	s_and_saveexec_b64 s[6:7], s[4:5]
	s_cbranch_execz .LBB0_1687
	v_lshl_add_u64 v[4:5], s[46:47], 0, v[104:105]
	v_lshlrev_b64 v[4:5], 9, v[4:5]
	v_lshl_add_u64 v[4:5], s[20:21], 0, v[4:5]
	s_lshl_b32 s0, s33, 2
	v_lshl_add_u64 v[4:5], v[4:5], 0, s[0:1]
	s_lshl_b32 s0, s54, 2
	v_lshl_add_u64 v[4:5], v[4:5], 0, s[0:1]
	v_pk_add_f32 v[0:1], v[0:1], v[2:3]
	global_store_dwordx2 v[4:5], v[0:1], off
	s_branch .LBB0_1687
